# s5_c scans: the 8 wave-local LDS reads of a 16-step block issued together behind the first, counted lgkmcnt waits
# baseline (speedup 1.0000x reference)
; #define LAS __attribute__((address_space(3)))
; __device__ __forceinline__ unsigned cvt_pk_bf16(float lo, float hi) { const bf16v2 v = __builtin_convertvector((f32x2){lo, hi}, bf16v2); return __builtin_bit_cast(unsigned, v); }
; __device__ __forceinline__ float bflo(unsigned w) { return __uint_as_float(w << 16); }
; __device__ __forceinline__ float bfhi(unsigned w) { return __uint_as_float(w & 0xffff0000u); }
; __device__ __forceinline__ u32x2 pack4(const f32x4 a) { u32x2 v; v.x = cvt_pk_bf16(a[0], a[1]); v.y = cvt_pk_bf16(a[2], a[3]); return v; }
; #define MFMA16(a, b, c) __builtin_amdgcn_mfma_f32_16x16x32_bf16((a), (b), (c), 0, 0, 0)
; __device__ __forceinline__ void s5_bu_block(const LAS bf16_t* UB, LAS bf16_t* XW, const bf16x8* bfrag, int blk, int g, int fr, int fq) {
;     bf16x8 af = (bf16x8){0, 0, 0, 0, 0, 0, 0, 0};
;     if (fq < 2) af = *(const LAS bf16x8*)(UB + (blk * 16 + fr) * 264 + g * 16 + fq * 8);
; #pragma unroll
;     for (int tile = 0; tile < 8; ++tile) { f32x4 acc = (f32x4){0.f, 0.f, 0.f, 0.f}; acc = MFMA16(bfrag[tile], af, acc);
;         *(LAS u32x2*)(XW + fr * 136 + tile * 16 + fq * 4) = pack4(acc); }
;     asm volatile("" ::: "memory");
; __device__ void s5_c_unit(LAS unsigned char* lds, KP& P_, int l, int bc) {
;     ...
;         for (int blk = 0; blk < 4; ++blk) {
;             s5_bu_block(UB, XW, bfrag, blk, g, fr, fq);
; #pragma unroll
;             for (int tl = 0; tl < 16; ++tl) { LAS unsigned* wp = (LAS unsigned*)(XW + tl * 136 + 2 * n); const unsigned w = *wp;
;                 const float nr = lam[0] * xr - lam[1] * xi + bflo(w), ni = lam[0] * xi + lam[1] * xr + bfhi(w); xr = nr; xi = ni; *wp = cvt_pk_bf16(xr, xi); }
;             asm volatile("" ::: "memory");
.LBB0_324:
	s_or_b64 exec, exec, s[14:15]
	s_waitcnt lgkmcnt(0)
	v_mfma_f32_16x16x32_bf16 v[90:93], v[16:19], v[56:59], 0
	v_add_u32_e32 v65, 0x8000, v96
	v_add_u32_e32 v89, 0x8400, v97
	s_nop 5
	v_cvt_pk_bf16_f32 v98, v90, v91
	v_cvt_pk_bf16_f32 v99, v92, v93
	v_mfma_f32_16x16x32_bf16 v[90:93], v[12:15], v[56:59], 0
	s_nop 7
	v_cvt_pk_bf16_f32 v90, v90, v91
	v_cvt_pk_bf16_f32 v91, v92, v93
	ds_write2_b64 v65, v[98:99], v[90:91] offset0:128 offset1:132
	v_mfma_f32_16x16x32_bf16 v[90:93], v[20:23], v[56:59], 0
	s_nop 7
	v_cvt_pk_bf16_f32 v98, v90, v91
	v_cvt_pk_bf16_f32 v99, v92, v93
	v_mfma_f32_16x16x32_bf16 v[90:93], v[8:11], v[56:59], 0
	s_nop 7
	v_cvt_pk_bf16_f32 v90, v90, v91
	v_cvt_pk_bf16_f32 v91, v92, v93
	ds_write2_b64 v65, v[98:99], v[90:91] offset0:136 offset1:140
	v_mfma_f32_16x16x32_bf16 v[90:93], v[32:35], v[56:59], 0
	s_nop 7
	v_cvt_pk_bf16_f32 v98, v90, v91
	v_cvt_pk_bf16_f32 v99, v92, v93
	v_mfma_f32_16x16x32_bf16 v[90:93], v[28:31], v[56:59], 0
	s_nop 7
	v_cvt_pk_bf16_f32 v90, v90, v91
	v_cvt_pk_bf16_f32 v91, v92, v93
	ds_write2_b64 v65, v[98:99], v[90:91] offset0:144 offset1:148
	v_mfma_f32_16x16x32_bf16 v[90:93], v[36:39], v[56:59], 0
	v_mfma_f32_16x16x32_bf16 v[56:59], v[24:27], v[56:59], 0
	s_nop 6
	v_cvt_pk_bf16_f32 v90, v90, v91
	v_cvt_pk_bf16_f32 v91, v92, v93
	v_cvt_pk_bf16_f32 v56, v56, v57
	v_cvt_pk_bf16_f32 v57, v58, v59
	ds_write2_b64 v65, v[90:91], v[56:57] offset0:152 offset1:156
	ds_read2_b32 v[56:57], v89 offset1:68
	v_add_u32_e32 v156, 0x8800, v97
	v_add_u32_e32 v158, 0x8c00, v97
	v_add_u32_e32 v170, 0x9000, v97
	ds_read2_b32 v[134:135], v89 offset0:136 offset1:204
	ds_read2_b32 v[142:143], v156 offset0:16 offset1:84
	ds_read2_b32 v[168:169], v156 offset0:152 offset1:220
	ds_read2_b32 v[174:175], v158 offset0:32 offset1:100
	ds_read2_b32 v[210:211], v158 offset0:168 offset1:236
	ds_read2_b32 v[216:217], v170 offset0:48 offset1:116
	ds_read2_b32 v[250:251], v170 offset0:184 offset1:252
	v_pk_mul_f32 v[58:59], v[84:85], v[0:1] op_sel_hi:[1,0]
	s_waitcnt lgkmcnt(7)
	v_lshlrev_b32_e32 v90, 16, v56
	v_pk_fma_f32 v[92:93], v[76:77], v[86:87], v[58:59] neg_lo:[0,0,1] neg_hi:[0,0,1]
	v_pk_fma_f32 v[58:59], v[76:77], v[86:87], v[58:59] op_sel_hi:[1,0,1]
	v_and_b32_e32 v91, 0xffff0000, v56
	v_mov_b32_e32 v93, v59
	v_pk_add_f32 v[58:59], v[92:93], v[90:91]
	v_lshlrev_b32_e32 v56, 16, v57
	v_pk_mul_f32 v[86:87], v[82:83], v[58:59]
	v_cvt_pk_bf16_f32 v0, v58, v59
	v_pk_fma_f32 v[90:91], v[80:81], v[58:59], v[86:87] op_sel:[0,0,1] op_sel_hi:[1,1,0] neg_lo:[0,0,1] neg_hi:[0,0,1]
	v_pk_fma_f32 v[58:59], v[80:81], v[58:59], v[86:87] op_sel:[0,0,1] op_sel_hi:[1,1,0]
	v_and_b32_e32 v57, 0xffff0000, v57
	v_mov_b32_e32 v91, v59
	v_pk_add_f32 v[56:57], v[90:91], v[56:57]
	s_nop 0
	v_cvt_pk_bf16_f32 v58, v56, v57
	ds_write2_b32 v89, v0, v58 offset1:68
	v_pk_mul_f32 v[90:91], v[82:83], v[56:57]
	s_waitcnt lgkmcnt(7)
	v_lshlrev_b32_e32 v86, 16, v134
	v_pk_fma_f32 v[92:93], v[80:81], v[56:57], v[90:91] op_sel:[0,0,1] op_sel_hi:[1,1,0] neg_lo:[0,0,1] neg_hi:[0,0,1]
	v_pk_fma_f32 v[56:57], v[80:81], v[56:57], v[90:91] op_sel:[0,0,1] op_sel_hi:[1,1,0]
	v_and_b32_e32 v87, 0xffff0000, v134
	v_mov_b32_e32 v93, v57
	v_pk_add_f32 v[56:57], v[92:93], v[86:87]
	v_lshlrev_b32_e32 v58, 16, v135
	v_pk_mul_f32 v[86:87], v[82:83], v[56:57]
	v_cvt_pk_bf16_f32 v0, v56, v57
	v_pk_fma_f32 v[90:91], v[80:81], v[56:57], v[86:87] op_sel:[0,0,1] op_sel_hi:[1,1,0] neg_lo:[0,0,1] neg_hi:[0,0,1]
	v_pk_fma_f32 v[56:57], v[80:81], v[56:57], v[86:87] op_sel:[0,0,1] op_sel_hi:[1,1,0]
	v_and_b32_e32 v59, 0xffff0000, v135
	v_mov_b32_e32 v91, v57
	v_pk_add_f32 v[56:57], v[90:91], v[58:59]
	v_add_u32_e32 v90, 0x8800, v97
	v_cvt_pk_bf16_f32 v58, v56, v57
	ds_write2_b32 v89, v0, v58 offset0:136 offset1:204
	v_pk_mul_f32 v[92:93], v[82:83], v[56:57]
	v_add_u32_e32 v91, 0x8c00, v97
	v_pk_fma_f32 v[98:99], v[80:81], v[56:57], v[92:93] op_sel:[0,0,1] op_sel_hi:[1,1,0] neg_lo:[0,0,1] neg_hi:[0,0,1]
	v_pk_fma_f32 v[56:57], v[80:81], v[56:57], v[92:93] op_sel:[0,0,1] op_sel_hi:[1,1,0]
	s_waitcnt lgkmcnt(7)
	v_lshlrev_b32_e32 v86, 16, v142
	v_and_b32_e32 v87, 0xffff0000, v142
	v_mov_b32_e32 v99, v57
	v_pk_add_f32 v[56:57], v[98:99], v[86:87]
	v_lshlrev_b32_e32 v58, 16, v143
	v_pk_mul_f32 v[86:87], v[82:83], v[56:57]
	v_cvt_pk_bf16_f32 v0, v56, v57
	v_pk_fma_f32 v[92:93], v[80:81], v[56:57], v[86:87] op_sel:[0,0,1] op_sel_hi:[1,1,0] neg_lo:[0,0,1] neg_hi:[0,0,1]
	v_pk_fma_f32 v[56:57], v[80:81], v[56:57], v[86:87] op_sel:[0,0,1] op_sel_hi:[1,1,0]
	v_and_b32_e32 v59, 0xffff0000, v143
	v_mov_b32_e32 v93, v57
	v_pk_add_f32 v[56:57], v[92:93], v[58:59]
	s_nop 0
	v_cvt_pk_bf16_f32 v58, v56, v57
	ds_write2_b32 v90, v0, v58 offset0:16 offset1:84
	v_pk_mul_f32 v[92:93], v[82:83], v[56:57]
	s_waitcnt lgkmcnt(7)
	v_lshlrev_b32_e32 v86, 16, v168
	v_pk_fma_f32 v[98:99], v[80:81], v[56:57], v[92:93] op_sel:[0,0,1] op_sel_hi:[1,1,0] neg_lo:[0,0,1] neg_hi:[0,0,1]
	v_pk_fma_f32 v[56:57], v[80:81], v[56:57], v[92:93] op_sel:[0,0,1] op_sel_hi:[1,1,0]
	v_and_b32_e32 v87, 0xffff0000, v168
	v_mov_b32_e32 v99, v57
	v_pk_add_f32 v[56:57], v[98:99], v[86:87]
	v_lshlrev_b32_e32 v58, 16, v169
	v_pk_mul_f32 v[86:87], v[82:83], v[56:57]
	v_cvt_pk_bf16_f32 v0, v56, v57
	v_pk_fma_f32 v[92:93], v[80:81], v[56:57], v[86:87] op_sel:[0,0,1] op_sel_hi:[1,1,0] neg_lo:[0,0,1] neg_hi:[0,0,1]
	v_pk_fma_f32 v[56:57], v[80:81], v[56:57], v[86:87] op_sel:[0,0,1] op_sel_hi:[1,1,0]
	v_and_b32_e32 v59, 0xffff0000, v169
	v_mov_b32_e32 v93, v57
	v_pk_add_f32 v[56:57], v[92:93], v[58:59]
	s_nop 0
	v_cvt_pk_bf16_f32 v58, v56, v57
	ds_write2_b32 v90, v0, v58 offset0:152 offset1:220
	v_pk_mul_f32 v[92:93], v[82:83], v[56:57]
	s_waitcnt lgkmcnt(7)
; #define LAS __attribute__((address_space(3)))
; __device__ __forceinline__ unsigned cvt_pk_bf16(float lo, float hi) { const bf16v2 v = __builtin_convertvector((f32x2){lo, hi}, bf16v2); return __builtin_bit_cast(unsigned, v); }
; __device__ __forceinline__ float bflo(unsigned w) { return __uint_as_float(w << 16); }
; __device__ __forceinline__ float bfhi(unsigned w) { return __uint_as_float(w & 0xffff0000u); }
; __device__ __forceinline__ u32x2 pack4(const f32x4 a) { u32x2 v; v.x = cvt_pk_bf16(a[0], a[1]); v.y = cvt_pk_bf16(a[2], a[3]); return v; }
; __device__ __forceinline__ float gelu_tanh(float x) { const float e = __builtin_amdgcn_exp2f(x * (-2.302208198f - 0.102943240f * x * x)); return x * __builtin_amdgcn_rcpf(1.0f + e); }
; #define MFMA16(a, b, c) __builtin_amdgcn_mfma_f32_16x16x32_bf16((a), (b), (c), 0, 0, 0)
; __device__ void s5_c_unit(LAS unsigned char* lds, KP& P_, int l, int bc) {
;     ...
;             for (int tl = 0; tl < 16; ++tl) { LAS unsigned* wp = (LAS unsigned*)(XW + tl * 136 + 2 * n); const unsigned w = *wp;
;                 const float nr = lam[0] * xr - lam[1] * xi + bflo(w), ni = lam[0] * xi + lam[1] * xr + bfhi(w); xr = nr; xi = ni; *wp = cvt_pk_bf16(xr, xi); }
;             asm volatile("" ::: "memory");
;             f32x4 acc = (f32x4){0.f, 0.f, 0.f, 0.f};
; #pragma unroll
;             for (int ks = 0; ks < 4; ++ks) { const bf16x8 b = *(const LAS bf16x8*)(XW + fr * 136 + ks * 32 + fq * 8); acc = MFMA16(cf[ks], b, acc); }
;             const int t = blk * 16 + fr; const u32x2 uraw = *(const LAS u32x2*)(UB + t * 264 + g * 16 + fq * 4);
;             const float uv[4] = {bflo(uraw.x), bfhi(uraw.x), bflo(uraw.y), bfhi(uraw.y)}; f32x4 y;
; #pragma unroll
;             for (int j = 0; j < 4; ++j) y[j] = gelu_tanh(acc[j] + dsk[j] * uv[j]);
;             *(LAS u32x2*)(YG + t * 264 + g * 16 + fq * 4) = pack4(y);
;             asm volatile("" ::: "memory");
	v_lshlrev_b32_e32 v86, 16, v174
	v_pk_fma_f32 v[98:99], v[80:81], v[56:57], v[92:93] op_sel:[0,0,1] op_sel_hi:[1,1,0] neg_lo:[0,0,1] neg_hi:[0,0,1]
	v_pk_fma_f32 v[56:57], v[80:81], v[56:57], v[92:93] op_sel:[0,0,1] op_sel_hi:[1,1,0]
	v_and_b32_e32 v87, 0xffff0000, v174
	v_mov_b32_e32 v99, v57
	v_pk_add_f32 v[56:57], v[98:99], v[86:87]
	v_lshlrev_b32_e32 v58, 16, v175
	v_pk_mul_f32 v[86:87], v[82:83], v[56:57]
	v_cvt_pk_bf16_f32 v0, v56, v57
	v_pk_fma_f32 v[92:93], v[80:81], v[56:57], v[86:87] op_sel:[0,0,1] op_sel_hi:[1,1,0] neg_lo:[0,0,1] neg_hi:[0,0,1]
	v_pk_fma_f32 v[56:57], v[80:81], v[56:57], v[86:87] op_sel:[0,0,1] op_sel_hi:[1,1,0]
	v_and_b32_e32 v59, 0xffff0000, v175
	v_mov_b32_e32 v93, v57
	v_pk_add_f32 v[56:57], v[92:93], v[58:59]
	s_nop 0
	v_cvt_pk_bf16_f32 v58, v56, v57
	ds_write2_b32 v91, v0, v58 offset0:32 offset1:100
	v_pk_mul_f32 v[92:93], v[82:83], v[56:57]
	s_waitcnt lgkmcnt(7)
	v_lshlrev_b32_e32 v86, 16, v210
	v_pk_fma_f32 v[98:99], v[80:81], v[56:57], v[92:93] op_sel:[0,0,1] op_sel_hi:[1,1,0] neg_lo:[0,0,1] neg_hi:[0,0,1]
	v_pk_fma_f32 v[56:57], v[80:81], v[56:57], v[92:93] op_sel:[0,0,1] op_sel_hi:[1,1,0]
	v_and_b32_e32 v87, 0xffff0000, v210
	v_mov_b32_e32 v99, v57
	v_pk_add_f32 v[56:57], v[98:99], v[86:87]
	v_lshlrev_b32_e32 v58, 16, v211
	v_pk_mul_f32 v[86:87], v[82:83], v[56:57]
	v_cvt_pk_bf16_f32 v0, v56, v57
	v_pk_fma_f32 v[92:93], v[80:81], v[56:57], v[86:87] op_sel:[0,0,1] op_sel_hi:[1,1,0] neg_lo:[0,0,1] neg_hi:[0,0,1]
	v_pk_fma_f32 v[56:57], v[80:81], v[56:57], v[86:87] op_sel:[0,0,1] op_sel_hi:[1,1,0]
	v_and_b32_e32 v59, 0xffff0000, v211
	v_mov_b32_e32 v93, v57
	v_pk_add_f32 v[56:57], v[92:93], v[58:59]
	v_add_u32_e32 v92, 0x9000, v97
	v_cvt_pk_bf16_f32 v58, v56, v57
	ds_write2_b32 v91, v0, v58 offset0:168 offset1:236
	v_pk_mul_f32 v[98:99], v[82:83], v[56:57]
	v_add_u32_e32 v93, v67, v3
	v_pk_fma_f32 v[100:101], v[80:81], v[56:57], v[98:99] op_sel:[0,0,1] op_sel_hi:[1,1,0] neg_lo:[0,0,1] neg_hi:[0,0,1]
	v_pk_fma_f32 v[56:57], v[80:81], v[56:57], v[98:99] op_sel:[0,0,1] op_sel_hi:[1,1,0]
	s_waitcnt lgkmcnt(7)
	v_lshlrev_b32_e32 v86, 16, v216
	v_and_b32_e32 v87, 0xffff0000, v216
	v_mov_b32_e32 v101, v57
	v_pk_add_f32 v[56:57], v[100:101], v[86:87]
	v_lshlrev_b32_e32 v58, 16, v217
	v_pk_mul_f32 v[86:87], v[82:83], v[56:57]
	v_cvt_pk_bf16_f32 v0, v56, v57
	v_pk_fma_f32 v[98:99], v[80:81], v[56:57], v[86:87] op_sel:[0,0,1] op_sel_hi:[1,1,0] neg_lo:[0,0,1] neg_hi:[0,0,1]
	v_pk_fma_f32 v[56:57], v[80:81], v[56:57], v[86:87] op_sel:[0,0,1] op_sel_hi:[1,1,0]
	v_and_b32_e32 v59, 0xffff0000, v217
	v_mov_b32_e32 v99, v57
	v_pk_add_f32 v[56:57], v[98:99], v[58:59]
	s_nop 0
	v_cvt_pk_bf16_f32 v58, v56, v57
	ds_write2_b32 v92, v0, v58 offset0:48 offset1:116
	v_pk_mul_f32 v[98:99], v[82:83], v[56:57]
	s_waitcnt lgkmcnt(7)
	v_lshlrev_b32_e32 v86, 16, v250
	v_pk_fma_f32 v[100:101], v[80:81], v[56:57], v[98:99] op_sel:[0,0,1] op_sel_hi:[1,1,0] neg_lo:[0,0,1] neg_hi:[0,0,1]
	v_pk_fma_f32 v[56:57], v[80:81], v[56:57], v[98:99] op_sel:[0,0,1] op_sel_hi:[1,1,0]
	v_and_b32_e32 v87, 0xffff0000, v250
	v_mov_b32_e32 v101, v57
	v_pk_add_f32 v[56:57], v[100:101], v[86:87]
	v_lshlrev_b32_e32 v58, 16, v251
	v_pk_mul_f32 v[86:87], v[82:83], v[56:57]
	v_cvt_pk_bf16_f32 v0, v56, v57
	v_pk_fma_f32 v[98:99], v[80:81], v[56:57], v[86:87] op_sel:[0,0,1] op_sel_hi:[1,1,0] neg_lo:[0,0,1] neg_hi:[0,0,1]
	v_pk_fma_f32 v[56:57], v[80:81], v[56:57], v[86:87] op_sel:[0,0,1] op_sel_hi:[1,1,0]
	v_and_b32_e32 v59, 0xffff0000, v251
	v_mov_b32_e32 v99, v57
	v_pk_add_f32 v[86:87], v[98:99], v[58:59]
	s_nop 0
	v_cvt_pk_bf16_f32 v56, v86, v87
	ds_write2_b32 v92, v0, v56 offset0:184 offset1:252
	ds_read_b128 v[56:59], v93 offset:33792
	ds_read_b128 v[98:101], v93 offset:33856
	v_add_u32_e32 v0, s23, v61
	ds_read_b64 v[102:103], v0
	s_waitcnt vmcnt(3) lgkmcnt(2)
	v_mfma_f32_16x16x32_bf16 v[56:59], v[40:43], v[56:59], 0
	v_add_u32_e32 v0, 0x10c00, v0
	s_addk_i32 s23, 0x2100
	s_waitcnt lgkmcnt(0)
	v_lshlrev_b32_e32 v104, 16, v102
	s_waitcnt vmcnt(2)
	v_mfma_f32_16x16x32_bf16 v[56:59], v[44:47], v[98:101], v[56:59]
	ds_read_b128 v[98:101], v93 offset:33920
	v_and_b32_e32 v105, 0xffff0000, v102
	s_cmpk_eq_u32 s23, 0x8400
	s_waitcnt vmcnt(1) lgkmcnt(0)
	v_mfma_f32_16x16x32_bf16 v[56:59], v[48:51], v[98:101], v[56:59]
	ds_read_b128 v[98:101], v93 offset:33984
	s_waitcnt vmcnt(0) lgkmcnt(0)
	v_mfma_f32_16x16x32_bf16 v[56:59], v[52:55], v[98:101], v[56:59]
	s_nop 7
	v_pk_fma_f32 v[56:57], v[242:243], v[104:105], v[56:57]
	s_nop 0
	v_mul_f32_e32 v98, 0x3dd2d3e8, v56
	v_mul_f32_e32 v99, 0x3dd2d3e8, v57
	v_fma_f32 v98, -v56, v98, s92
	v_fma_f32 v99, -v57, v99, s92
	v_mul_f32_e32 v98, v56, v98
	v_mul_f32_e32 v99, v57, v99
	v_exp_f32_e32 v98, v98
	v_exp_f32_e32 v99, v99
	v_add_f32_e32 v98, 1.0, v98
	v_add_f32_e32 v99, 1.0, v99
	v_rcp_f32_e32 v98, v98
	v_rcp_f32_e32 v99, v99
	s_nop 0
	v_pk_mul_f32 v[56:57], v[56:57], v[98:99]
	v_lshlrev_b32_e32 v98, 16, v103
	v_and_b32_e32 v99, 0xffff0000, v103
	v_pk_fma_f32 v[58:59], v[244:245], v[98:99], v[58:59]
	v_cvt_pk_bf16_f32 v56, v56, v57
	v_mul_f32_e32 v98, 0x3dd2d3e8, v58
	v_mul_f32_e32 v99, 0x3dd2d3e8, v59
	v_fma_f32 v98, -v58, v98, s92
	v_fma_f32 v99, -v59, v99, s92
	v_mul_f32_e32 v98, v58, v98
	v_mul_f32_e32 v99, v59, v99
	v_exp_f32_e32 v98, v98
	v_exp_f32_e32 v99, v99
	v_add_f32_e32 v98, 1.0, v98
	v_add_f32_e32 v99, 1.0, v99
	v_rcp_f32_e32 v98, v98
	v_rcp_f32_e32 v99, v99
	s_nop 0
	v_pk_mul_f32 v[58:59], v[58:59], v[98:99]
	s_nop 0
	v_cvt_pk_bf16_f32 v57, v58, v59
	ds_write_b64 v0, v[56:57]
	v_mov_b32_e32 v0, v87
	s_cbranch_scc1 .LBB0_327

; #define LAS __attribute__((address_space(3)))
; __device__ __forceinline__ unsigned cvt_pk_bf16(float lo, float hi) { const bf16v2 v = __builtin_convertvector((f32x2){lo, hi}, bf16v2); return __builtin_bit_cast(unsigned, v); }
; __device__ __forceinline__ float bflo(unsigned w) { return __uint_as_float(w << 16); }
; __device__ __forceinline__ float bfhi(unsigned w) { return __uint_as_float(w & 0xffff0000u); }
; __device__ __forceinline__ u32x2 pack4(const f32x4 a) { u32x2 v; v.x = cvt_pk_bf16(a[0], a[1]); v.y = cvt_pk_bf16(a[2], a[3]); return v; }
; #define MFMA16(a, b, c) __builtin_amdgcn_mfma_f32_16x16x32_bf16((a), (b), (c), 0, 0, 0)
; __device__ __forceinline__ void s5_bu_block(const LAS bf16_t* UB, LAS bf16_t* XW, const bf16x8* bfrag, int blk, int g, int fr, int fq) {
;     bf16x8 af = (bf16x8){0, 0, 0, 0, 0, 0, 0, 0};
;     if (fq < 2) af = *(const LAS bf16x8*)(UB + (blk * 16 + fr) * 264 + g * 16 + fq * 8);
; #pragma unroll
;     for (int tile = 0; tile < 8; ++tile) { f32x4 acc = (f32x4){0.f, 0.f, 0.f, 0.f}; acc = MFMA16(bfrag[tile], af, acc);
;         *(LAS u32x2*)(XW + fr * 136 + tile * 16 + fq * 4) = pack4(acc); }
;     asm volatile("" ::: "memory");
; __device__ void s5_c_unit(LAS unsigned char* lds, KP& P_, int l, int bc) {
;     ...
;         for (int blk = 0; blk < 4; ++blk) {
;             s5_bu_block(UB, XW, bfrag, blk, g, fr, fq);
; #pragma unroll
;             for (int tl = 0; tl < 16; ++tl) { LAS unsigned* wp = (LAS unsigned*)(XW + tl * 136 + 2 * n); const unsigned w = *wp;
;                 const float nr = lam[0] * xr - lam[1] * xi + bflo(w), ni = lam[0] * xi + lam[1] * xr + bfhi(w); xr = nr; xi = ni; *wp = cvt_pk_bf16(xr, xi); }
;             asm volatile("" ::: "memory");
.LBB0_336:
	s_or_b64 exec, exec, s[14:15]
	s_waitcnt lgkmcnt(0)
	v_mfma_f32_16x16x32_bf16 v[80:83], v[16:19], v[56:59], 0
	s_nop 7
	v_cvt_pk_bf16_f32 v84, v80, v81
	v_cvt_pk_bf16_f32 v85, v82, v83
	v_mfma_f32_16x16x32_bf16 v[80:83], v[12:15], v[56:59], 0
	s_nop 7
	v_cvt_pk_bf16_f32 v80, v80, v81
	v_cvt_pk_bf16_f32 v81, v82, v83
	ds_write2_b64 v65, v[84:85], v[80:81] offset0:128 offset1:132
	v_mfma_f32_16x16x32_bf16 v[80:83], v[20:23], v[56:59], 0
	s_nop 7
	v_cvt_pk_bf16_f32 v84, v80, v81
	v_cvt_pk_bf16_f32 v85, v82, v83
	v_mfma_f32_16x16x32_bf16 v[80:83], v[8:11], v[56:59], 0
	s_nop 7
	v_cvt_pk_bf16_f32 v80, v80, v81
	v_cvt_pk_bf16_f32 v81, v82, v83
	ds_write2_b64 v65, v[84:85], v[80:81] offset0:136 offset1:140
	v_mfma_f32_16x16x32_bf16 v[80:83], v[32:35], v[56:59], 0
	s_nop 7
	v_cvt_pk_bf16_f32 v84, v80, v81
	v_cvt_pk_bf16_f32 v85, v82, v83
	v_mfma_f32_16x16x32_bf16 v[80:83], v[28:31], v[56:59], 0
	s_nop 7
	v_cvt_pk_bf16_f32 v80, v80, v81
	v_cvt_pk_bf16_f32 v81, v82, v83
	ds_write2_b64 v65, v[84:85], v[80:81] offset0:144 offset1:148
	v_mfma_f32_16x16x32_bf16 v[80:83], v[36:39], v[56:59], 0
	v_mfma_f32_16x16x32_bf16 v[56:59], v[24:27], v[56:59], 0
	s_nop 6
	v_cvt_pk_bf16_f32 v80, v80, v81
	v_cvt_pk_bf16_f32 v81, v82, v83
	v_cvt_pk_bf16_f32 v56, v56, v57
	v_cvt_pk_bf16_f32 v57, v58, v59
	ds_write2_b64 v65, v[80:81], v[56:57] offset0:152 offset1:156
	ds_read2_b32 v[56:57], v89 offset1:68
	ds_read2_b32 v[134:135], v89 offset0:136 offset1:204
	ds_read2_b32 v[142:143], v90 offset0:16 offset1:84
	ds_read2_b32 v[168:169], v90 offset0:152 offset1:220
	ds_read2_b32 v[174:175], v91 offset0:32 offset1:100
	ds_read2_b32 v[210:211], v91 offset0:168 offset1:236
	ds_read2_b32 v[216:217], v92 offset0:48 offset1:116
	ds_read2_b32 v[250:251], v92 offset0:184 offset1:252
	v_pk_mul_f32 v[58:59], v[74:75], v[0:1] op_sel_hi:[1,0]
	s_waitcnt lgkmcnt(7)
	v_lshlrev_b32_e32 v80, 16, v56
	v_pk_fma_f32 v[82:83], v[66:67], v[76:77], v[58:59] neg_lo:[0,0,1] neg_hi:[0,0,1]
	v_pk_fma_f32 v[58:59], v[66:67], v[76:77], v[58:59] op_sel_hi:[1,0,1]
	v_and_b32_e32 v81, 0xffff0000, v56
	v_mov_b32_e32 v83, v59
	v_pk_add_f32 v[58:59], v[82:83], v[80:81]
	v_lshlrev_b32_e32 v56, 16, v57
	v_pk_mul_f32 v[76:77], v[72:73], v[58:59]
	v_cvt_pk_bf16_f32 v0, v58, v59
	v_pk_fma_f32 v[80:81], v[70:71], v[58:59], v[76:77] op_sel:[0,0,1] op_sel_hi:[1,1,0] neg_lo:[0,0,1] neg_hi:[0,0,1]
	v_pk_fma_f32 v[58:59], v[70:71], v[58:59], v[76:77] op_sel:[0,0,1] op_sel_hi:[1,1,0]
	v_and_b32_e32 v57, 0xffff0000, v57
	v_mov_b32_e32 v81, v59
	v_pk_add_f32 v[56:57], v[80:81], v[56:57]
	s_nop 0
	v_cvt_pk_bf16_f32 v58, v56, v57
	ds_write2_b32 v89, v0, v58 offset1:68
	v_pk_mul_f32 v[80:81], v[72:73], v[56:57]
	s_waitcnt lgkmcnt(7)
	v_lshlrev_b32_e32 v76, 16, v134
	v_pk_fma_f32 v[82:83], v[70:71], v[56:57], v[80:81] op_sel:[0,0,1] op_sel_hi:[1,1,0] neg_lo:[0,0,1] neg_hi:[0,0,1]
	v_pk_fma_f32 v[56:57], v[70:71], v[56:57], v[80:81] op_sel:[0,0,1] op_sel_hi:[1,1,0]
	v_and_b32_e32 v77, 0xffff0000, v134
	v_mov_b32_e32 v83, v57
	v_pk_add_f32 v[56:57], v[82:83], v[76:77]
	v_lshlrev_b32_e32 v58, 16, v135
	v_pk_mul_f32 v[76:77], v[72:73], v[56:57]
	v_cvt_pk_bf16_f32 v0, v56, v57
	v_pk_fma_f32 v[80:81], v[70:71], v[56:57], v[76:77] op_sel:[0,0,1] op_sel_hi:[1,1,0] neg_lo:[0,0,1] neg_hi:[0,0,1]
	v_pk_fma_f32 v[56:57], v[70:71], v[56:57], v[76:77] op_sel:[0,0,1] op_sel_hi:[1,1,0]
	v_and_b32_e32 v59, 0xffff0000, v135
	v_mov_b32_e32 v81, v57
	v_pk_add_f32 v[56:57], v[80:81], v[58:59]
	s_nop 0
	v_cvt_pk_bf16_f32 v58, v56, v57
	ds_write2_b32 v89, v0, v58 offset0:136 offset1:204
	v_pk_mul_f32 v[80:81], v[72:73], v[56:57]
	s_waitcnt lgkmcnt(7)
	v_lshlrev_b32_e32 v76, 16, v142
	v_pk_fma_f32 v[82:83], v[70:71], v[56:57], v[80:81] op_sel:[0,0,1] op_sel_hi:[1,1,0] neg_lo:[0,0,1] neg_hi:[0,0,1]
	v_pk_fma_f32 v[56:57], v[70:71], v[56:57], v[80:81] op_sel:[0,0,1] op_sel_hi:[1,1,0]
	v_and_b32_e32 v77, 0xffff0000, v142
	v_mov_b32_e32 v83, v57
	v_pk_add_f32 v[56:57], v[82:83], v[76:77]
	v_lshlrev_b32_e32 v58, 16, v143
	v_pk_mul_f32 v[76:77], v[72:73], v[56:57]
	v_cvt_pk_bf16_f32 v0, v56, v57
	v_pk_fma_f32 v[80:81], v[70:71], v[56:57], v[76:77] op_sel:[0,0,1] op_sel_hi:[1,1,0] neg_lo:[0,0,1] neg_hi:[0,0,1]
	v_pk_fma_f32 v[56:57], v[70:71], v[56:57], v[76:77] op_sel:[0,0,1] op_sel_hi:[1,1,0]
	v_and_b32_e32 v59, 0xffff0000, v143
	v_mov_b32_e32 v81, v57
	v_pk_add_f32 v[56:57], v[80:81], v[58:59]
	s_nop 0
	v_cvt_pk_bf16_f32 v58, v56, v57
	ds_write2_b32 v90, v0, v58 offset0:16 offset1:84
	v_pk_mul_f32 v[80:81], v[72:73], v[56:57]
	s_waitcnt lgkmcnt(7)
	v_lshlrev_b32_e32 v76, 16, v168
	v_pk_fma_f32 v[82:83], v[70:71], v[56:57], v[80:81] op_sel:[0,0,1] op_sel_hi:[1,1,0] neg_lo:[0,0,1] neg_hi:[0,0,1]
	v_pk_fma_f32 v[56:57], v[70:71], v[56:57], v[80:81] op_sel:[0,0,1] op_sel_hi:[1,1,0]
	v_and_b32_e32 v77, 0xffff0000, v168
	v_mov_b32_e32 v83, v57
	v_pk_add_f32 v[56:57], v[82:83], v[76:77]
	v_lshlrev_b32_e32 v58, 16, v169
	v_pk_mul_f32 v[76:77], v[72:73], v[56:57]
	v_cvt_pk_bf16_f32 v0, v56, v57
	v_pk_fma_f32 v[80:81], v[70:71], v[56:57], v[76:77] op_sel:[0,0,1] op_sel_hi:[1,1,0] neg_lo:[0,0,1] neg_hi:[0,0,1]
	v_pk_fma_f32 v[56:57], v[70:71], v[56:57], v[76:77] op_sel:[0,0,1] op_sel_hi:[1,1,0]
	v_and_b32_e32 v59, 0xffff0000, v169
	v_mov_b32_e32 v81, v57
	v_pk_add_f32 v[56:57], v[80:81], v[58:59]
	s_nop 0
	v_cvt_pk_bf16_f32 v58, v56, v57
	ds_write2_b32 v90, v0, v58 offset0:152 offset1:220
	v_pk_mul_f32 v[80:81], v[72:73], v[56:57]
	s_waitcnt lgkmcnt(7)
; #define LAS __attribute__((address_space(3)))
; __device__ __forceinline__ unsigned cvt_pk_bf16(float lo, float hi) { const bf16v2 v = __builtin_convertvector((f32x2){lo, hi}, bf16v2); return __builtin_bit_cast(unsigned, v); }
; __device__ __forceinline__ float bflo(unsigned w) { return __uint_as_float(w << 16); }
; __device__ __forceinline__ float bfhi(unsigned w) { return __uint_as_float(w & 0xffff0000u); }
; __device__ __forceinline__ u32x2 pack4(const f32x4 a) { u32x2 v; v.x = cvt_pk_bf16(a[0], a[1]); v.y = cvt_pk_bf16(a[2], a[3]); return v; }
; __device__ __forceinline__ float gelu_tanh(float x) { const float e = __builtin_amdgcn_exp2f(x * (-2.302208198f - 0.102943240f * x * x)); return x * __builtin_amdgcn_rcpf(1.0f + e); }
; #define MFMA16(a, b, c) __builtin_amdgcn_mfma_f32_16x16x32_bf16((a), (b), (c), 0, 0, 0)
; __device__ void s5_c_unit(LAS unsigned char* lds, KP& P_, int l, int bc) {
;     ...
;             for (int tl = 0; tl < 16; ++tl) { LAS unsigned* wp = (LAS unsigned*)(XW + tl * 136 + 2 * n); const unsigned w = *wp;
;                 const float nr = lam[0] * xr - lam[1] * xi + bflo(w), ni = lam[0] * xi + lam[1] * xr + bfhi(w); xr = nr; xi = ni; *wp = cvt_pk_bf16(xr, xi); }
;             asm volatile("" ::: "memory");
;             f32x4 acc = (f32x4){0.f, 0.f, 0.f, 0.f};
; #pragma unroll
;             for (int ks = 0; ks < 4; ++ks) { const bf16x8 b = *(const LAS bf16x8*)(XW + fr * 136 + ks * 32 + fq * 8); acc = MFMA16(cf[ks], b, acc); }
;             const int t = blk * 16 + fr; const u32x2 uraw = *(const LAS u32x2*)(UB + t * 264 + g * 16 + fq * 4);
;             const float uv[4] = {bflo(uraw.x), bfhi(uraw.x), bflo(uraw.y), bfhi(uraw.y)}; f32x4 y;
; #pragma unroll
;             for (int j = 0; j < 4; ++j) y[j] = gelu_tanh(acc[j] + dsk[j] * uv[j]);
;             *(LAS u32x2*)(YG + t * 264 + g * 16 + fq * 4) = pack4(y);
;             asm volatile("" ::: "memory");
	v_lshlrev_b32_e32 v76, 16, v174
	v_pk_fma_f32 v[82:83], v[70:71], v[56:57], v[80:81] op_sel:[0,0,1] op_sel_hi:[1,1,0] neg_lo:[0,0,1] neg_hi:[0,0,1]
	v_pk_fma_f32 v[56:57], v[70:71], v[56:57], v[80:81] op_sel:[0,0,1] op_sel_hi:[1,1,0]
	v_and_b32_e32 v77, 0xffff0000, v174
	v_mov_b32_e32 v83, v57
	v_pk_add_f32 v[56:57], v[82:83], v[76:77]
	v_lshlrev_b32_e32 v58, 16, v175
	v_pk_mul_f32 v[76:77], v[72:73], v[56:57]
	v_cvt_pk_bf16_f32 v0, v56, v57
	v_pk_fma_f32 v[80:81], v[70:71], v[56:57], v[76:77] op_sel:[0,0,1] op_sel_hi:[1,1,0] neg_lo:[0,0,1] neg_hi:[0,0,1]
	v_pk_fma_f32 v[56:57], v[70:71], v[56:57], v[76:77] op_sel:[0,0,1] op_sel_hi:[1,1,0]
	v_and_b32_e32 v59, 0xffff0000, v175
	v_mov_b32_e32 v81, v57
	v_pk_add_f32 v[56:57], v[80:81], v[58:59]
	s_nop 0
	v_cvt_pk_bf16_f32 v58, v56, v57
	ds_write2_b32 v91, v0, v58 offset0:32 offset1:100
	v_pk_mul_f32 v[80:81], v[72:73], v[56:57]
	s_waitcnt lgkmcnt(7)
	v_lshlrev_b32_e32 v76, 16, v210
	v_pk_fma_f32 v[82:83], v[70:71], v[56:57], v[80:81] op_sel:[0,0,1] op_sel_hi:[1,1,0] neg_lo:[0,0,1] neg_hi:[0,0,1]
	v_pk_fma_f32 v[56:57], v[70:71], v[56:57], v[80:81] op_sel:[0,0,1] op_sel_hi:[1,1,0]
	v_and_b32_e32 v77, 0xffff0000, v210
	v_mov_b32_e32 v83, v57
	v_pk_add_f32 v[56:57], v[82:83], v[76:77]
	v_lshlrev_b32_e32 v58, 16, v211
	v_pk_mul_f32 v[76:77], v[72:73], v[56:57]
	v_cvt_pk_bf16_f32 v0, v56, v57
	v_pk_fma_f32 v[80:81], v[70:71], v[56:57], v[76:77] op_sel:[0,0,1] op_sel_hi:[1,1,0] neg_lo:[0,0,1] neg_hi:[0,0,1]
	v_pk_fma_f32 v[56:57], v[70:71], v[56:57], v[76:77] op_sel:[0,0,1] op_sel_hi:[1,1,0]
	v_and_b32_e32 v59, 0xffff0000, v211
	v_mov_b32_e32 v81, v57
	v_pk_add_f32 v[56:57], v[80:81], v[58:59]
	s_nop 0
	v_cvt_pk_bf16_f32 v58, v56, v57
	ds_write2_b32 v91, v0, v58 offset0:168 offset1:236
	v_pk_mul_f32 v[80:81], v[72:73], v[56:57]
	s_waitcnt lgkmcnt(7)
	v_lshlrev_b32_e32 v76, 16, v216
	v_pk_fma_f32 v[82:83], v[70:71], v[56:57], v[80:81] op_sel:[0,0,1] op_sel_hi:[1,1,0] neg_lo:[0,0,1] neg_hi:[0,0,1]
	v_pk_fma_f32 v[56:57], v[70:71], v[56:57], v[80:81] op_sel:[0,0,1] op_sel_hi:[1,1,0]
	v_and_b32_e32 v77, 0xffff0000, v216
	v_mov_b32_e32 v83, v57
	v_pk_add_f32 v[56:57], v[82:83], v[76:77]
	v_lshlrev_b32_e32 v58, 16, v217
	v_pk_mul_f32 v[76:77], v[72:73], v[56:57]
	v_cvt_pk_bf16_f32 v0, v56, v57
	v_pk_fma_f32 v[80:81], v[70:71], v[56:57], v[76:77] op_sel:[0,0,1] op_sel_hi:[1,1,0] neg_lo:[0,0,1] neg_hi:[0,0,1]
	v_pk_fma_f32 v[56:57], v[70:71], v[56:57], v[76:77] op_sel:[0,0,1] op_sel_hi:[1,1,0]
	v_and_b32_e32 v59, 0xffff0000, v217
	v_mov_b32_e32 v81, v57
	v_pk_add_f32 v[56:57], v[80:81], v[58:59]
	s_nop 0
	v_cvt_pk_bf16_f32 v58, v56, v57
	ds_write2_b32 v92, v0, v58 offset0:48 offset1:116
	v_pk_mul_f32 v[80:81], v[72:73], v[56:57]
	s_waitcnt lgkmcnt(7)
	v_lshlrev_b32_e32 v76, 16, v250
	v_pk_fma_f32 v[82:83], v[70:71], v[56:57], v[80:81] op_sel:[0,0,1] op_sel_hi:[1,1,0] neg_lo:[0,0,1] neg_hi:[0,0,1]
	v_pk_fma_f32 v[56:57], v[70:71], v[56:57], v[80:81] op_sel:[0,0,1] op_sel_hi:[1,1,0]
	v_and_b32_e32 v77, 0xffff0000, v250
	v_mov_b32_e32 v83, v57
	v_pk_add_f32 v[56:57], v[82:83], v[76:77]
	v_lshlrev_b32_e32 v58, 16, v251
	v_pk_mul_f32 v[76:77], v[72:73], v[56:57]
	v_cvt_pk_bf16_f32 v0, v56, v57
	v_pk_fma_f32 v[80:81], v[70:71], v[56:57], v[76:77] op_sel:[0,0,1] op_sel_hi:[1,1,0] neg_lo:[0,0,1] neg_hi:[0,0,1]
	v_pk_fma_f32 v[56:57], v[70:71], v[56:57], v[76:77] op_sel:[0,0,1] op_sel_hi:[1,1,0]
	v_and_b32_e32 v59, 0xffff0000, v251
	v_mov_b32_e32 v81, v57
	v_pk_add_f32 v[76:77], v[80:81], v[58:59]
	s_nop 0
	v_cvt_pk_bf16_f32 v56, v76, v77
	ds_write2_b32 v92, v0, v56 offset0:184 offset1:252
	ds_read_b128 v[56:59], v93 offset:33792
	ds_read_b128 v[80:83], v93 offset:33856
	v_add_u32_e32 v0, s23, v61
	ds_read_b64 v[84:85], v0 offset:256
	s_waitcnt vmcnt(3) lgkmcnt(2)
	v_mfma_f32_16x16x32_bf16 v[56:59], v[40:43], v[56:59], 0
	v_add_u32_e32 v0, 0x10d00, v0
	s_addk_i32 s23, 0x2100
	s_waitcnt lgkmcnt(0)
	v_lshlrev_b32_e32 v86, 16, v84
	s_waitcnt vmcnt(2)
	v_mfma_f32_16x16x32_bf16 v[56:59], v[44:47], v[80:83], v[56:59]
	ds_read_b128 v[80:83], v93 offset:33920
	v_and_b32_e32 v87, 0xffff0000, v84
	s_cmpk_eq_u32 s23, 0x8400
	s_waitcnt vmcnt(1) lgkmcnt(0)
	v_mfma_f32_16x16x32_bf16 v[56:59], v[48:51], v[80:83], v[56:59]
	ds_read_b128 v[80:83], v93 offset:33984
	s_waitcnt vmcnt(0) lgkmcnt(0)
	v_mfma_f32_16x16x32_bf16 v[56:59], v[52:55], v[80:83], v[56:59]
	s_nop 7
	v_pk_fma_f32 v[56:57], v[246:247], v[86:87], v[56:57]
	s_nop 0
	v_mul_f32_e32 v79, 0x3dd2d3e8, v56
	v_fma_f32 v79, -v56, v79, s92
	v_mul_f32_e32 v79, v56, v79
	v_exp_f32_e32 v79, v79
	s_nop 0
	v_add_f32_e32 v79, 1.0, v79
	v_rcp_f32_e32 v80, v79
	v_mul_f32_e32 v79, 0x3dd2d3e8, v57
	v_fma_f32 v79, -v57, v79, s92
	v_mul_f32_e32 v79, v57, v79
	v_exp_f32_e32 v79, v79
	s_nop 0
	v_add_f32_e32 v79, 1.0, v79
	v_rcp_f32_e32 v81, v79
	s_nop 0
	v_pk_mul_f32 v[56:57], v[56:57], v[80:81]
	v_lshlrev_b32_e32 v80, 16, v85
	v_and_b32_e32 v81, 0xffff0000, v85
	v_pk_fma_f32 v[58:59], v[248:249], v[80:81], v[58:59]
	v_cvt_pk_bf16_f32 v56, v56, v57
	v_mul_f32_e32 v79, 0x3dd2d3e8, v58
	v_fma_f32 v79, -v58, v79, s92
	v_mul_f32_e32 v79, v58, v79
	v_exp_f32_e32 v79, v79
	s_nop 0
	v_add_f32_e32 v79, 1.0, v79
	v_rcp_f32_e32 v80, v79
	v_mul_f32_e32 v79, 0x3dd2d3e8, v59
	v_fma_f32 v79, -v59, v79, s92
	v_mul_f32_e32 v79, v59, v79
	v_exp_f32_e32 v79, v79
	s_nop 0
	v_add_f32_e32 v79, 1.0, v79
	v_rcp_f32_e32 v81, v79
	s_nop 0
	v_pk_mul_f32 v[58:59], v[58:59], v[80:81]
	s_nop 0
	v_cvt_pk_bf16_f32 v57, v58, v59
	ds_write_b64 v0, v[56:57]
	v_mov_b32_e32 v0, v77
	s_cbranch_scc1 .LBB0_339
